# cache policy: the FFN-in epilogue's 8 output stores (hidden activations, written once) marked nt
# baseline (speedup 1.0000x reference)
.LBB0_641:
	v_mul_f32_e32 v149, 0xbfb8aa3b, v120
	v_exp_f32_e32 v149, v149
	v_lshl_add_u32 v148, s22, 8, v144
	v_lshl_or_b32 v142, s20, 7, v146
	v_ashrrev_i32_e32 v143, 31, v142
	v_add_f32_e32 v149, 1.0, v149
	v_rcp_f32_e32 v152, v149
	v_mul_f32_e32 v149, 0xbfb8aa3b, v121
	v_exp_f32_e32 v149, v149
	v_mov_b64_e32 v[140:141], s[8:9]
	v_mad_i64_i32 v[150:151], s[20:21], v148, s71, v[140:141]
	v_add_f32_e32 v149, 1.0, v149
	v_rcp_f32_e32 v153, v149
	v_lshlrev_b64 v[142:143], 1, v[142:143]
	v_lshl_add_u64 v[150:151], v[150:151], 0, v[142:143]
	s_mov_b64 s[22:23], -1
	v_pk_mul_f32 v[120:121], v[120:121], v[152:153]
	s_andn2_b64 vcc, exec, s[6:7]
	v_pk_mul_f32 v[120:121], v[120:121], v[124:125]
	s_nop 0
	v_cvt_pk_bf16_f32 v120, v120, v121
	v_mul_f32_e32 v121, 0xbfb8aa3b, v122
	v_exp_f32_e32 v121, v121
	s_nop 0
	v_add_f32_e32 v121, 1.0, v121
	v_rcp_f32_e32 v124, v121
	v_mul_f32_e32 v121, 0xbfb8aa3b, v123
	v_exp_f32_e32 v121, v121
	s_nop 0
	v_add_f32_e32 v121, 1.0, v121
	v_rcp_f32_e32 v125, v121
	s_nop 0
	v_pk_mul_f32 v[122:123], v[122:123], v[124:125]
	s_nop 0
	v_pk_mul_f32 v[122:123], v[122:123], v[126:127]
	s_nop 0
	v_cvt_pk_bf16_f32 v121, v122, v123
	v_mul_f32_e32 v122, 0xbfb8aa3b, v112
	v_mul_f32_e32 v123, 0xbfb8aa3b, v113
	v_exp_f32_e32 v122, v122
	v_exp_f32_e32 v123, v123
	v_add_f32_e32 v122, 1.0, v122
	v_add_f32_e32 v123, 1.0, v123
	v_rcp_f32_e32 v122, v122
	v_rcp_f32_e32 v123, v123
	s_nop 0
	v_pk_mul_f32 v[112:113], v[112:113], v[122:123]
	s_nop 0
	v_pk_mul_f32 v[112:113], v[112:113], v[116:117]
	s_nop 0
	v_cvt_pk_bf16_f32 v122, v112, v113
	v_mul_f32_e32 v112, 0xbfb8aa3b, v114
	v_mul_f32_e32 v113, 0xbfb8aa3b, v115
	v_exp_f32_e32 v112, v112
	v_exp_f32_e32 v113, v113
	v_add_f32_e32 v112, 1.0, v112
	v_add_f32_e32 v113, 1.0, v113
	v_rcp_f32_e32 v112, v112
	v_rcp_f32_e32 v113, v113
	s_nop 0
	v_pk_mul_f32 v[112:113], v[114:115], v[112:113]
	v_mul_f32_e32 v114, 0xbfb8aa3b, v104
	v_mul_f32_e32 v115, 0xbfb8aa3b, v105
	v_exp_f32_e32 v114, v114
	v_exp_f32_e32 v115, v115
	v_pk_mul_f32 v[112:113], v[112:113], v[118:119]
	v_add_f32_e32 v114, 1.0, v114
	v_add_f32_e32 v115, 1.0, v115
	v_rcp_f32_e32 v114, v114
	v_rcp_f32_e32 v115, v115
	v_cvt_pk_bf16_f32 v123, v112, v113
	v_or_b32_e32 v112, 16, v148
	v_mad_i64_i32 v[112:113], s[20:21], v112, s71, v[140:141]
	v_pk_mul_f32 v[104:105], v[104:105], v[114:115]
	v_lshl_add_u64 v[112:113], v[112:113], 0, v[142:143]
	v_pk_mul_f32 v[104:105], v[104:105], v[108:109]
	global_store_dwordx4 v[150:151], v[120:123], off nt
	v_cvt_pk_bf16_f32 v104, v104, v105
	v_mul_f32_e32 v105, 0xbfb8aa3b, v106
	v_exp_f32_e32 v105, v105
	s_nop 0
	v_add_f32_e32 v105, 1.0, v105
	v_rcp_f32_e32 v108, v105
	v_mul_f32_e32 v105, 0xbfb8aa3b, v107
	v_exp_f32_e32 v105, v105
	s_nop 0
	v_add_f32_e32 v105, 1.0, v105
	v_rcp_f32_e32 v109, v105
	s_nop 0
	v_pk_mul_f32 v[106:107], v[106:107], v[108:109]
	s_nop 0
	v_pk_mul_f32 v[106:107], v[106:107], v[110:111]
	s_nop 0
	v_cvt_pk_bf16_f32 v105, v106, v107
	v_mul_f32_e32 v106, 0xbfb8aa3b, v96
	v_mul_f32_e32 v107, 0xbfb8aa3b, v97
	v_exp_f32_e32 v106, v106
	v_exp_f32_e32 v107, v107
	v_add_f32_e32 v106, 1.0, v106
	v_add_f32_e32 v107, 1.0, v107
	v_rcp_f32_e32 v106, v106
	v_rcp_f32_e32 v107, v107
	s_nop 0
	v_pk_mul_f32 v[96:97], v[96:97], v[106:107]
	s_nop 0
	v_pk_mul_f32 v[96:97], v[96:97], v[100:101]
	s_nop 0
	v_cvt_pk_bf16_f32 v106, v96, v97
	v_mul_f32_e32 v96, 0xbfb8aa3b, v98
	v_mul_f32_e32 v97, 0xbfb8aa3b, v99
	v_exp_f32_e32 v96, v96
	v_exp_f32_e32 v97, v97
	v_add_f32_e32 v96, 1.0, v96
	v_add_f32_e32 v97, 1.0, v97
	v_rcp_f32_e32 v96, v96
	v_rcp_f32_e32 v97, v97
	s_nop 0
	v_pk_mul_f32 v[96:97], v[98:99], v[96:97]
	v_mul_f32_e32 v98, 0xbfb8aa3b, v88
	v_mul_f32_e32 v99, 0xbfb8aa3b, v89
	v_exp_f32_e32 v98, v98
	v_exp_f32_e32 v99, v99
	v_pk_mul_f32 v[96:97], v[96:97], v[102:103]
	v_add_f32_e32 v98, 1.0, v98
	v_add_f32_e32 v99, 1.0, v99
	v_rcp_f32_e32 v98, v98
	v_rcp_f32_e32 v99, v99
	v_cvt_pk_bf16_f32 v107, v96, v97
	v_or_b32_e32 v96, 32, v148
	v_mad_i64_i32 v[96:97], s[20:21], v96, s71, v[140:141]
	v_pk_mul_f32 v[88:89], v[88:89], v[98:99]
	v_lshl_add_u64 v[96:97], v[96:97], 0, v[142:143]
	v_pk_mul_f32 v[88:89], v[88:89], v[92:93]
	global_store_dwordx4 v[112:113], v[104:107], off nt
	v_cvt_pk_bf16_f32 v88, v88, v89
	v_mul_f32_e32 v89, 0xbfb8aa3b, v90
	v_exp_f32_e32 v89, v89
	s_nop 0
	v_add_f32_e32 v89, 1.0, v89
	v_rcp_f32_e32 v92, v89
	v_mul_f32_e32 v89, 0xbfb8aa3b, v91
	v_exp_f32_e32 v89, v89
	s_nop 0
	v_add_f32_e32 v89, 1.0, v89
	v_rcp_f32_e32 v93, v89
	s_nop 0
	v_pk_mul_f32 v[90:91], v[90:91], v[92:93]
	s_nop 0
	v_pk_mul_f32 v[90:91], v[90:91], v[94:95]
	s_nop 0
	v_cvt_pk_bf16_f32 v89, v90, v91
	v_mul_f32_e32 v90, 0xbfb8aa3b, v80
	v_mul_f32_e32 v91, 0xbfb8aa3b, v81
	v_exp_f32_e32 v90, v90
	v_exp_f32_e32 v91, v91
	v_add_f32_e32 v90, 1.0, v90
	v_add_f32_e32 v91, 1.0, v91
	v_rcp_f32_e32 v90, v90
	v_rcp_f32_e32 v91, v91
	s_nop 0
	v_pk_mul_f32 v[80:81], v[80:81], v[90:91]
	s_nop 0
	v_pk_mul_f32 v[80:81], v[80:81], v[84:85]
	s_nop 0
	v_cvt_pk_bf16_f32 v90, v80, v81
	v_mul_f32_e32 v80, 0xbfb8aa3b, v82
	v_mul_f32_e32 v81, 0xbfb8aa3b, v83
	v_exp_f32_e32 v80, v80
	v_exp_f32_e32 v81, v81
	v_add_f32_e32 v80, 1.0, v80
	v_add_f32_e32 v81, 1.0, v81
	v_rcp_f32_e32 v80, v80
	v_rcp_f32_e32 v81, v81
	s_nop 0
	v_pk_mul_f32 v[80:81], v[82:83], v[80:81]
	v_mul_f32_e32 v82, 0xbfb8aa3b, v72
	v_mul_f32_e32 v83, 0xbfb8aa3b, v73
	v_exp_f32_e32 v82, v82
	v_exp_f32_e32 v83, v83
	v_pk_mul_f32 v[80:81], v[80:81], v[86:87]
	v_add_f32_e32 v82, 1.0, v82
	v_add_f32_e32 v83, 1.0, v83
	v_rcp_f32_e32 v82, v82
	v_rcp_f32_e32 v83, v83
	v_cvt_pk_bf16_f32 v91, v80, v81
	v_or_b32_e32 v80, 48, v148
	v_mad_i64_i32 v[80:81], s[20:21], v80, s71, v[140:141]
	v_pk_mul_f32 v[72:73], v[72:73], v[82:83]
	v_lshl_add_u64 v[80:81], v[80:81], 0, v[142:143]
	v_pk_mul_f32 v[72:73], v[72:73], v[76:77]
	global_store_dwordx4 v[96:97], v[88:91], off nt
	v_cvt_pk_bf16_f32 v72, v72, v73
	v_mul_f32_e32 v73, 0xbfb8aa3b, v74
	v_exp_f32_e32 v73, v73
	s_nop 0
	v_add_f32_e32 v73, 1.0, v73
	v_rcp_f32_e32 v76, v73
	v_mul_f32_e32 v73, 0xbfb8aa3b, v75
	v_exp_f32_e32 v73, v73
	s_nop 0
	v_add_f32_e32 v73, 1.0, v73
	v_rcp_f32_e32 v77, v73
	s_nop 0
	v_pk_mul_f32 v[74:75], v[74:75], v[76:77]
	s_nop 0
	v_pk_mul_f32 v[74:75], v[74:75], v[78:79]
	s_nop 0
	v_cvt_pk_bf16_f32 v73, v74, v75
	v_mul_f32_e32 v74, 0xbfb8aa3b, v64
	v_mul_f32_e32 v75, 0xbfb8aa3b, v65
	v_exp_f32_e32 v74, v74
	v_exp_f32_e32 v75, v75
	v_add_f32_e32 v74, 1.0, v74
	v_add_f32_e32 v75, 1.0, v75
	v_rcp_f32_e32 v74, v74
	v_rcp_f32_e32 v75, v75
	s_nop 0
	v_pk_mul_f32 v[64:65], v[64:65], v[74:75]
	s_nop 0
	v_pk_mul_f32 v[64:65], v[64:65], v[68:69]
	s_nop 0
	v_cvt_pk_bf16_f32 v74, v64, v65
	v_mul_f32_e32 v64, 0xbfb8aa3b, v66
	v_mul_f32_e32 v65, 0xbfb8aa3b, v67
	v_exp_f32_e32 v64, v64
	v_exp_f32_e32 v65, v65
	v_add_f32_e32 v64, 1.0, v64
	v_add_f32_e32 v65, 1.0, v65
	v_rcp_f32_e32 v64, v64
	v_rcp_f32_e32 v65, v65
	s_nop 0
	v_pk_mul_f32 v[64:65], v[66:67], v[64:65]
	v_mul_f32_e32 v66, 0xbfb8aa3b, v56
	v_mul_f32_e32 v67, 0xbfb8aa3b, v57
	v_exp_f32_e32 v66, v66
	v_exp_f32_e32 v67, v67
	v_pk_mul_f32 v[64:65], v[64:65], v[70:71]
	v_add_f32_e32 v66, 1.0, v66
	v_add_f32_e32 v67, 1.0, v67
	v_rcp_f32_e32 v66, v66
	v_rcp_f32_e32 v67, v67
	v_cvt_pk_bf16_f32 v75, v64, v65
	v_add_u32_e32 v64, 0x80, v148
	v_mad_i64_i32 v[64:65], s[20:21], v64, s71, v[140:141]
	v_pk_mul_f32 v[56:57], v[56:57], v[66:67]
	v_lshl_add_u64 v[64:65], v[64:65], 0, v[142:143]
	v_pk_mul_f32 v[56:57], v[56:57], v[60:61]
	global_store_dwordx4 v[80:81], v[72:75], off nt
	v_cvt_pk_bf16_f32 v56, v56, v57
	v_mul_f32_e32 v57, 0xbfb8aa3b, v58
	v_exp_f32_e32 v57, v57
	s_nop 0
	v_add_f32_e32 v57, 1.0, v57
	v_rcp_f32_e32 v60, v57
	v_mul_f32_e32 v57, 0xbfb8aa3b, v59
	v_exp_f32_e32 v57, v57
	s_nop 0
	v_add_f32_e32 v57, 1.0, v57
	v_rcp_f32_e32 v61, v57
	s_nop 0
	v_pk_mul_f32 v[58:59], v[58:59], v[60:61]
	s_nop 0
	v_pk_mul_f32 v[58:59], v[58:59], v[62:63]
	s_nop 0
	v_cvt_pk_bf16_f32 v57, v58, v59
	v_mul_f32_e32 v58, 0xbfb8aa3b, v48
	v_mul_f32_e32 v59, 0xbfb8aa3b, v49
	v_exp_f32_e32 v58, v58
	v_exp_f32_e32 v59, v59
	v_add_f32_e32 v58, 1.0, v58
	v_add_f32_e32 v59, 1.0, v59
	v_rcp_f32_e32 v58, v58
	v_rcp_f32_e32 v59, v59
	s_nop 0
	v_pk_mul_f32 v[48:49], v[48:49], v[58:59]
	s_nop 0
	v_pk_mul_f32 v[48:49], v[48:49], v[52:53]
	s_nop 0
	v_cvt_pk_bf16_f32 v58, v48, v49
	v_mul_f32_e32 v48, 0xbfb8aa3b, v50
	v_mul_f32_e32 v49, 0xbfb8aa3b, v51
	v_exp_f32_e32 v48, v48
	v_exp_f32_e32 v49, v49
	v_add_f32_e32 v48, 1.0, v48
	v_add_f32_e32 v49, 1.0, v49
	v_rcp_f32_e32 v48, v48
	v_rcp_f32_e32 v49, v49
	s_nop 0
	v_pk_mul_f32 v[48:49], v[50:51], v[48:49]
	v_mul_f32_e32 v50, 0xbfb8aa3b, v40
	v_mul_f32_e32 v51, 0xbfb8aa3b, v41
	v_exp_f32_e32 v50, v50
	v_exp_f32_e32 v51, v51
	v_pk_mul_f32 v[48:49], v[48:49], v[54:55]
	v_add_f32_e32 v50, 1.0, v50
	v_add_f32_e32 v51, 1.0, v51
	v_rcp_f32_e32 v50, v50
	v_rcp_f32_e32 v51, v51
	v_cvt_pk_bf16_f32 v59, v48, v49
	v_add_u32_e32 v48, 0x90, v148
	v_mad_i64_i32 v[48:49], s[20:21], v48, s71, v[140:141]
	v_pk_mul_f32 v[40:41], v[40:41], v[50:51]
	v_lshl_add_u64 v[48:49], v[48:49], 0, v[142:143]
	v_pk_mul_f32 v[40:41], v[40:41], v[44:45]
	global_store_dwordx4 v[64:65], v[56:59], off nt
	v_cvt_pk_bf16_f32 v40, v40, v41
	v_mul_f32_e32 v41, 0xbfb8aa3b, v42
	v_exp_f32_e32 v41, v41
	s_nop 0
	v_add_f32_e32 v41, 1.0, v41
	v_rcp_f32_e32 v44, v41
	v_mul_f32_e32 v41, 0xbfb8aa3b, v43
	v_exp_f32_e32 v41, v41
	s_nop 0
	v_add_f32_e32 v41, 1.0, v41
	v_rcp_f32_e32 v45, v41
	s_nop 0
	v_pk_mul_f32 v[42:43], v[42:43], v[44:45]
	s_nop 0
	v_pk_mul_f32 v[42:43], v[42:43], v[46:47]
	s_nop 0
	v_cvt_pk_bf16_f32 v41, v42, v43
	v_mul_f32_e32 v42, 0xbfb8aa3b, v32
	v_mul_f32_e32 v43, 0xbfb8aa3b, v33
	v_exp_f32_e32 v42, v42
	v_exp_f32_e32 v43, v43
	v_add_f32_e32 v42, 1.0, v42
	v_add_f32_e32 v43, 1.0, v43
	v_rcp_f32_e32 v42, v42
	v_rcp_f32_e32 v43, v43
	s_nop 0
	v_pk_mul_f32 v[32:33], v[32:33], v[42:43]
	s_nop 0
	v_pk_mul_f32 v[32:33], v[32:33], v[36:37]
	s_nop 0
	v_cvt_pk_bf16_f32 v42, v32, v33
	v_mul_f32_e32 v32, 0xbfb8aa3b, v34
	v_mul_f32_e32 v33, 0xbfb8aa3b, v35
	v_exp_f32_e32 v32, v32
	v_exp_f32_e32 v33, v33
	v_add_f32_e32 v32, 1.0, v32
	v_add_f32_e32 v33, 1.0, v33
	v_rcp_f32_e32 v32, v32
	v_rcp_f32_e32 v33, v33
	s_nop 0
	v_pk_mul_f32 v[32:33], v[34:35], v[32:33]
	v_mul_f32_e32 v34, 0xbfb8aa3b, v24
	v_mul_f32_e32 v35, 0xbfb8aa3b, v25
	v_exp_f32_e32 v34, v34
	v_exp_f32_e32 v35, v35
	v_pk_mul_f32 v[32:33], v[32:33], v[38:39]
	v_add_f32_e32 v34, 1.0, v34
	v_add_f32_e32 v35, 1.0, v35
	v_rcp_f32_e32 v34, v34
	v_rcp_f32_e32 v35, v35
	v_cvt_pk_bf16_f32 v43, v32, v33
	v_add_u32_e32 v32, 0xa0, v148
	v_mad_i64_i32 v[32:33], s[20:21], v32, s71, v[140:141]
	v_pk_mul_f32 v[24:25], v[24:25], v[34:35]
	v_lshl_add_u64 v[32:33], v[32:33], 0, v[142:143]
	v_pk_mul_f32 v[24:25], v[24:25], v[28:29]
	global_store_dwordx4 v[48:49], v[40:43], off nt
	v_cvt_pk_bf16_f32 v24, v24, v25
	v_mul_f32_e32 v25, 0xbfb8aa3b, v26
	v_exp_f32_e32 v25, v25
	s_nop 0
	v_add_f32_e32 v25, 1.0, v25
	v_rcp_f32_e32 v28, v25
	v_mul_f32_e32 v25, 0xbfb8aa3b, v27
	v_exp_f32_e32 v25, v25
	s_nop 0
	v_add_f32_e32 v25, 1.0, v25
	v_rcp_f32_e32 v29, v25
	s_nop 0
	v_pk_mul_f32 v[26:27], v[26:27], v[28:29]
	s_nop 0
	v_pk_mul_f32 v[26:27], v[26:27], v[30:31]
	s_nop 0
	v_cvt_pk_bf16_f32 v25, v26, v27
	v_mul_f32_e32 v26, 0xbfb8aa3b, v16
	v_mul_f32_e32 v27, 0xbfb8aa3b, v17
	v_exp_f32_e32 v26, v26
	v_exp_f32_e32 v27, v27
	v_add_f32_e32 v26, 1.0, v26
	v_add_f32_e32 v27, 1.0, v27
	v_rcp_f32_e32 v26, v26
	v_rcp_f32_e32 v27, v27
	s_nop 0
	v_pk_mul_f32 v[16:17], v[16:17], v[26:27]
	s_nop 0
	v_pk_mul_f32 v[16:17], v[16:17], v[20:21]
	s_nop 0
	v_cvt_pk_bf16_f32 v26, v16, v17
	v_mul_f32_e32 v16, 0xbfb8aa3b, v18
	v_mul_f32_e32 v17, 0xbfb8aa3b, v19
	v_exp_f32_e32 v16, v16
	v_exp_f32_e32 v17, v17
	v_add_f32_e32 v16, 1.0, v16
	v_add_f32_e32 v17, 1.0, v17
	v_rcp_f32_e32 v16, v16
	v_rcp_f32_e32 v17, v17
	s_nop 0
	v_pk_mul_f32 v[16:17], v[18:19], v[16:17]
	v_mul_f32_e32 v18, 0xbfb8aa3b, v8
	v_mul_f32_e32 v19, 0xbfb8aa3b, v9
	v_exp_f32_e32 v18, v18
	v_exp_f32_e32 v19, v19
	v_pk_mul_f32 v[16:17], v[16:17], v[22:23]
	v_add_f32_e32 v18, 1.0, v18
	v_add_f32_e32 v19, 1.0, v19
	v_rcp_f32_e32 v18, v18
	v_rcp_f32_e32 v19, v19
	v_cvt_pk_bf16_f32 v27, v16, v17
	v_add_u32_e32 v16, 0xb0, v148
	v_mad_i64_i32 v[16:17], s[20:21], v16, s71, v[140:141]
	v_pk_mul_f32 v[8:9], v[8:9], v[18:19]
	v_lshl_add_u64 v[16:17], v[16:17], 0, v[142:143]
	v_pk_mul_f32 v[8:9], v[8:9], v[12:13]
	global_store_dwordx4 v[32:33], v[24:27], off nt
	v_cvt_pk_bf16_f32 v8, v8, v9
	v_mul_f32_e32 v9, 0xbfb8aa3b, v10
	v_exp_f32_e32 v9, v9
	s_nop 0
	v_add_f32_e32 v9, 1.0, v9
	v_rcp_f32_e32 v12, v9
	v_mul_f32_e32 v9, 0xbfb8aa3b, v11
	v_exp_f32_e32 v9, v9
	s_nop 0
	v_add_f32_e32 v9, 1.0, v9
	v_rcp_f32_e32 v13, v9
	s_nop 0
	v_pk_mul_f32 v[10:11], v[10:11], v[12:13]
	s_nop 0
	v_pk_mul_f32 v[10:11], v[10:11], v[14:15]
	s_nop 0
	v_cvt_pk_bf16_f32 v9, v10, v11
	v_mul_f32_e32 v10, 0xbfb8aa3b, v0
	v_mul_f32_e32 v11, 0xbfb8aa3b, v1
	v_exp_f32_e32 v10, v10
	v_exp_f32_e32 v11, v11
	v_add_f32_e32 v10, 1.0, v10
	v_add_f32_e32 v11, 1.0, v11
	v_rcp_f32_e32 v10, v10
	v_rcp_f32_e32 v11, v11
	s_nop 0
	v_pk_mul_f32 v[0:1], v[0:1], v[10:11]
	s_nop 0
	v_pk_mul_f32 v[0:1], v[0:1], v[4:5]
	s_nop 0
	v_cvt_pk_bf16_f32 v10, v0, v1
	v_mul_f32_e32 v0, 0xbfb8aa3b, v2
	v_mul_f32_e32 v1, 0xbfb8aa3b, v3
	v_exp_f32_e32 v0, v0
	v_exp_f32_e32 v1, v1
	v_add_f32_e32 v0, 1.0, v0
	v_add_f32_e32 v1, 1.0, v1
	v_rcp_f32_e32 v0, v0
	v_rcp_f32_e32 v1, v1
	s_nop 0
	v_pk_mul_f32 v[0:1], v[2:3], v[0:1]
	s_nop 0
	v_pk_mul_f32 v[0:1], v[0:1], v[6:7]
	s_nop 0
	v_cvt_pk_bf16_f32 v11, v0, v1
	global_store_dwordx4 v[16:17], v[8:11], off nt
	s_cbranch_vccnz .LBB0_634
	s_andn2_b64 vcc, exec, s[2:3]
	v_mov_b32 v120, 0
	v_mov_b32 v112, 0
	v_mov_b32 v104, 0
	v_mov_b32 v96, 0
	v_mov_b32 v88, 0
	v_mov_b32 v80, 0
	v_mov_b32 v72, 0
	v_mov_b32 v64, 0
	v_mov_b32 v124, 0
	v_mov_b32 v116, 0
	v_mov_b32 v108, 0
	v_mov_b32 v100, 0
	v_mov_b32 v92, 0
	v_mov_b32 v84, 0
	v_mov_b32 v76, 0
	v_mov_b32 v68, 0
	v_mov_b32 v56, 0
	v_mov_b32 v48, 0
	v_mov_b32 v40, 0
	v_mov_b32 v32, 0
	v_mov_b32 v24, 0
	v_mov_b32 v16, 0
	v_mov_b32 v8, 0
	v_mov_b32 v0, 0
	v_mov_b32 v60, 0
	v_mov_b32 v52, 0
	v_mov_b32 v44, 0
	v_mov_b32 v36, 0
	v_mov_b32 v28, 0
	v_mov_b32 v20, 0
	v_mov_b32 v12, 0
	v_mov_b32 v4, 0
	s_cbranch_vccnz .LBB0_633
	s_barrier
	s_branch .LBB0_633
